# b26 + static prio raise for waves 4-7 in ATTN + ATTN item-code packed f32 unpacked (combination)
# speedup vs baseline: 1.0123x; 1.0016x over previous
.LBB0_1269:
	ds_bpermute_b32 v0, v155, v121
	ds_read_b128 v[236:239], v210
	ds_read_b128 v[240:243], v210 offset:1024
	ds_read_b128 v[244:247], v210 offset:2048
	ds_read_b128 v[248:251], v210 offset:3072
	ds_read_b128 v[134:137], v210 offset:4096
	ds_read_b128 v[138:141], v210 offset:5120
	ds_read_b128 v[142:145], v210 offset:6144
	ds_read_b128 v[146:149], v210 offset:7168
	v_mov_b32_e32 v123, v32
	v_mov_b32_e32 v125, v32
	v_mov_b32_e32 v127, v32
	v_mov_b32_e32 v129, v32
	s_waitcnt lgkmcnt(8)
	v_add_f32_e32 v0, v121, v0
	v_div_scale_f32 v1, s[0:1], v0, v0, v106
	v_rcp_f32_e32 v2, v1
	s_ashr_i32 s1, s39, 31
	s_add_u32 s0, s46, s39
	s_addc_u32 s1, s47, s1
	v_fma_f32 v3, -v1, v2, 1.0
	v_fmac_f32_e32 v2, v3, v2
	v_div_scale_f32 v3, vcc, v106, v0, v106
	v_mul_f32_e32 v4, v3, v2
	v_fma_f32 v5, -v1, v4, v3
	v_fmac_f32_e32 v4, v5, v2
	v_fma_f32 v1, -v1, v4, v3
	v_div_fmas_f32 v1, v1, v2, v4
	v_div_fixup_f32 v0, v1, v0, v106
	s_or_b64 s[0:1], s[0:1], s[60:61]
	s_lshl_b64 s[0:1], s[0:1], 11
	s_add_u32 s2, s26, s0
	s_addc_u32 s3, s27, s1
	s_lshl_b64 s[0:1], s[48:49], 1
	s_add_u32 s0, s2, s0
	s_addc_u32 s1, s3, s1
	v_mov_b32_e32 v121, v32
	s_add_i32 s38, s38, 1
	s_cmp_eq_u32 s38, s72
	s_waitcnt lgkmcnt(7)
	v_fmac_f32_e32 v236, v64, v0
	v_fmac_f32_e32 v237, v65, v0
	v_fmac_f32_e32 v238, v66, v0
	v_fmac_f32_e32 v239, v67, v0
	v_cvt_pk_bf16_f32 v2, v236, v237
	v_cvt_pk_bf16_f32 v3, v238, v239
	s_waitcnt lgkmcnt(6)
	v_fmac_f32_e32 v240, v68, v0
	v_fmac_f32_e32 v241, v69, v0
	v_fmac_f32_e32 v242, v70, v0
	v_fmac_f32_e32 v243, v71, v0
	v_cvt_pk_bf16_f32 v8, v240, v241
	v_cvt_pk_bf16_f32 v9, v242, v243
	s_waitcnt lgkmcnt(5)
	v_fmac_f32_e32 v244, v72, v0
	v_fmac_f32_e32 v245, v73, v0
	v_fmac_f32_e32 v246, v74, v0
	v_fmac_f32_e32 v247, v75, v0
	v_cvt_pk_bf16_f32 v10, v244, v245
	v_cvt_pk_bf16_f32 v11, v246, v247
	s_waitcnt lgkmcnt(4)
	v_fmac_f32_e32 v248, v76, v0
	v_fmac_f32_e32 v249, v77, v0
	v_fmac_f32_e32 v250, v78, v0
	v_fmac_f32_e32 v251, v79, v0
	v_cvt_pk_bf16_f32 v12, v248, v249
	v_cvt_pk_bf16_f32 v13, v250, v251
	s_waitcnt lgkmcnt(3)
	v_fmac_f32_e32 v134, v48, v0
	v_fmac_f32_e32 v135, v49, v0
	v_fmac_f32_e32 v136, v50, v0
	v_fmac_f32_e32 v137, v51, v0
	v_cvt_pk_bf16_f32 v14, v134, v135
	v_cvt_pk_bf16_f32 v15, v136, v137
	s_waitcnt lgkmcnt(2)
	v_fmac_f32_e32 v138, v52, v0
	v_fmac_f32_e32 v139, v53, v0
	v_fmac_f32_e32 v140, v54, v0
	v_fmac_f32_e32 v141, v55, v0
	v_cvt_pk_bf16_f32 v16, v138, v139
	v_cvt_pk_bf16_f32 v17, v140, v141
	s_waitcnt lgkmcnt(1)
	v_fmac_f32_e32 v142, v56, v0
	v_fmac_f32_e32 v143, v57, v0
	v_fmac_f32_e32 v144, v58, v0
	v_fmac_f32_e32 v145, v59, v0
	v_cvt_pk_bf16_f32 v18, v142, v143
	v_cvt_pk_bf16_f32 v19, v144, v145
	s_waitcnt lgkmcnt(0)
	v_fmac_f32_e32 v146, v60, v0
	v_fmac_f32_e32 v147, v61, v0
	v_fmac_f32_e32 v148, v62, v0
	v_fmac_f32_e32 v149, v63, v0
	s_nop 0
	v_cvt_pk_bf16_f32 v4, v146, v147
	v_cvt_pk_bf16_f32 v5, v148, v149
	ds_write2_b64 v206, v[2:3], v[8:9] offset1:2
	ds_write2_b64 v206, v[10:11], v[12:13] offset0:4 offset1:6
	ds_write2_b64 v206, v[14:15], v[16:17] offset0:8 offset1:10
	ds_write2_b64 v206, v[18:19], v[4:5] offset0:12 offset1:14
	s_waitcnt lgkmcnt(0)
	ds_read_b128 v[236:239], v207
	ds_read_b128 v[240:243], v208
	ds_read_b128 v[244:247], v208 offset:1152
	ds_read_b128 v[248:251], v208 offset:2304
	v_lshl_add_u64 v[4:5], s[0:1], 0, v[120:121]
	v_lshl_add_u64 v[6:7], v[4:5], 0, v[122:123]
	v_lshl_add_u64 v[8:9], v[4:5], 0, v[124:125]
	v_lshl_add_u64 v[10:11], v[4:5], 0, v[126:127]
	v_lshl_add_u64 v[4:5], v[4:5], 0, v[128:129]
	s_waitcnt lgkmcnt(3)
	global_store_dwordx4 v[6:7], v[236:239], off
	s_waitcnt lgkmcnt(2)
	global_store_dwordx4 v[8:9], v[240:243], off
	s_waitcnt lgkmcnt(1)
	global_store_dwordx4 v[10:11], v[244:247], off
	s_waitcnt lgkmcnt(0)
	global_store_dwordx4 v[4:5], v[248:251], off
	s_cbranch_scc1 .LBB0_1476

.LBB0_1453:
	s_cmp_lg_u32 s6, s2
	s_cbranch_scc1 .LBB0_1455
	ds_bpermute_b32 v0, v155, v121
	ds_read_b128 v[236:239], v210
	ds_read_b128 v[240:243], v210 offset:1024
	ds_read_b128 v[244:247], v210 offset:2048
	ds_read_b128 v[248:251], v210 offset:3072
	ds_read_b128 v[134:137], v210 offset:4096
	ds_read_b128 v[138:141], v210 offset:5120
	ds_read_b128 v[142:145], v210 offset:6144
	ds_read_b128 v[146:149], v210 offset:7168
	v_mov_b32_e32 v46, v32
	v_mov_b32_e32 v47, v32
	v_mov_b32_e32 v33, v32
	v_mov_b32_e32 v34, v32
	v_mov_b32_e32 v35, v32
	v_mov_b32_e32 v36, v32
	v_mov_b32_e32 v37, v32
	v_mov_b32_e32 v38, v32
	v_mov_b32_e32 v39, v32
	v_mov_b32_e32 v40, v32
	v_mov_b32_e32 v41, v32
	v_mov_b32_e32 v42, v32
	v_mov_b32_e32 v43, v32
	v_mov_b32_e32 v44, v32
	v_mov_b32_e32 v45, v32
	s_waitcnt lgkmcnt(8)
	v_add_f32_e32 v0, v121, v0
	v_div_scale_f32 v1, s[0:1], v0, v0, v105
	v_rcp_f32_e32 v2, v1
	s_nop 0
	v_fma_f32 v3, -v1, v2, 1.0
	v_fmac_f32_e32 v2, v3, v2
	v_div_scale_f32 v3, vcc, v105, v0, v105
	v_mul_f32_e32 v4, v3, v2
	v_fma_f32 v5, -v1, v4, v3
	v_fmac_f32_e32 v4, v5, v2
	v_fma_f32 v1, -v1, v4, v3
	v_div_fmas_f32 v1, v1, v2, v4
	v_div_fixup_f32 v0, v1, v0, v105
	v_mov_b32_e32 v121, 0
	v_mov_b32_e32 v123, 0xff800000
	s_waitcnt lgkmcnt(7)
	v_fmac_f32_e32 v236, v64, v0
	v_fmac_f32_e32 v237, v65, v0
	v_fmac_f32_e32 v238, v66, v0
	v_fmac_f32_e32 v239, v67, v0
	s_waitcnt lgkmcnt(6)
	v_fmac_f32_e32 v240, v68, v0
	v_fmac_f32_e32 v241, v69, v0
	v_fmac_f32_e32 v242, v70, v0
	v_fmac_f32_e32 v243, v71, v0
	s_waitcnt lgkmcnt(5)
	v_fmac_f32_e32 v244, v72, v0
	v_fmac_f32_e32 v245, v73, v0
	v_fmac_f32_e32 v246, v74, v0
	v_fmac_f32_e32 v247, v75, v0
	s_waitcnt lgkmcnt(4)
	v_fmac_f32_e32 v248, v76, v0
	v_fmac_f32_e32 v249, v77, v0
	v_fmac_f32_e32 v250, v78, v0
	v_fmac_f32_e32 v251, v79, v0
	s_waitcnt lgkmcnt(3)
	v_fmac_f32_e32 v134, v48, v0
	v_fmac_f32_e32 v135, v49, v0
	v_fmac_f32_e32 v136, v50, v0
	v_fmac_f32_e32 v137, v51, v0
	s_waitcnt lgkmcnt(2)
	v_fmac_f32_e32 v138, v52, v0
	v_fmac_f32_e32 v139, v53, v0
	v_fmac_f32_e32 v140, v54, v0
	v_fmac_f32_e32 v141, v55, v0
	s_waitcnt lgkmcnt(1)
	v_fmac_f32_e32 v142, v56, v0
	v_fmac_f32_e32 v143, v57, v0
	v_fmac_f32_e32 v144, v58, v0
	v_fmac_f32_e32 v145, v59, v0
	s_waitcnt lgkmcnt(0)
	v_fmac_f32_e32 v146, v60, v0
	v_fmac_f32_e32 v147, v61, v0
	v_fmac_f32_e32 v148, v62, v0
	v_fmac_f32_e32 v149, v63, v0
	ds_write_b128 v210, v[236:239]
	ds_write_b128 v210, v[240:243] offset:1024
	ds_write_b128 v210, v[244:247] offset:2048
	ds_write_b128 v210, v[248:251] offset:3072
	ds_write_b128 v210, v[134:137] offset:4096
	ds_write_b128 v210, v[138:141] offset:5120
	ds_write_b128 v210, v[142:145] offset:6144
	ds_write_b128 v210, v[146:149] offset:7168
	v_mov_b64_e32 v[78:79], v[46:47]
	v_mov_b64_e32 v[76:77], v[44:45]
	v_mov_b64_e32 v[74:75], v[42:43]
	v_mov_b64_e32 v[72:73], v[40:41]
	v_mov_b64_e32 v[70:71], v[38:39]
	v_mov_b64_e32 v[68:69], v[36:37]
	v_mov_b64_e32 v[66:67], v[34:35]
	v_mov_b64_e32 v[64:65], v[32:33]
	v_mov_b64_e32 v[62:63], v[46:47]
	v_mov_b64_e32 v[60:61], v[44:45]
	v_mov_b64_e32 v[58:59], v[42:43]
	v_mov_b64_e32 v[56:57], v[40:41]
	v_mov_b64_e32 v[54:55], v[38:39]
	v_mov_b64_e32 v[52:53], v[36:37]
	v_mov_b64_e32 v[50:51], v[34:35]
	v_mov_b64_e32 v[48:49], v[32:33]
